# ssd_out: D-skip scalar of the wave's head loaded above the conv compute instead of after the barrier (one exposed round trip per head group removed)
# speedup vs baseline: 1.0017x; 1.0015x over previous
.LBB0_570:
	v_add_co_u32_e32 v6, vcc, 0x2000, v4
	s_nop 1
	v_addc_co_u32_e32 v7, vcc, 0, v5, vcc
	global_load_dwordx2 v[118:119], v[4:5], off offset:3584
	global_load_dwordx2 v[120:121], v[6:7], off offset:2048
	v_add_co_u32_e32 v6, vcc, 0x4000, v4
	s_nop 1
	v_addc_co_u32_e32 v7, vcc, 0, v5, vcc
	global_load_dwordx2 v[122:123], v[6:7], off offset:512
	v_add_co_u32_e32 v6, vcc, 0x5000, v4
	s_nop 1
	v_addc_co_u32_e32 v7, vcc, 0, v5, vcc
	global_load_dwordx2 v[148:149], v[6:7], off offset:3072
	v_add_co_u32_e32 v6, vcc, 0x7000, v4
	s_nop 1
	v_addc_co_u32_e32 v7, vcc, 0, v5, vcc
	global_load_dwordx2 v[108:109], v[6:7], off offset:1536
	v_add_co_u32_e32 v6, vcc, 0x9000, v4
	s_xor_b64 s[2:3], s[10:11], -1
	s_nop 0
	v_addc_co_u32_e32 v7, vcc, 0, v5, vcc
	global_load_dwordx2 v[110:111], v[6:7], off
	v_add_co_u32_e32 v6, vcc, s35, v4
	s_lshl_b32 s10, s12, 2
	s_nop 0
	v_addc_co_u32_e32 v7, vcc, 0, v5, vcc
	global_load_dwordx2 v[112:113], v[6:7], off offset:2560
	v_add_co_u32_e32 v6, vcc, s36, v4
	s_add_i32 s12, s68, s10
	s_nop 0
	v_addc_co_u32_e32 v7, vcc, 0, v5, vcc
	global_load_dwordx2 v[116:117], v[6:7], off offset:1024
	v_add_co_u32_e32 v6, vcc, 0xd000, v4
	s_ashr_i32 s13, s12, 31
	s_nop 0
	v_addc_co_u32_e32 v7, vcc, 0, v5, vcc
	global_load_dwordx2 v[96:97], v[6:7], off offset:3584
	v_add_co_u32_e32 v6, vcc, 0xf000, v4
	s_lshl_b64 s[12:13], s[12:13], 14
	s_nop 0
	v_addc_co_u32_e32 v7, vcc, 0, v5, vcc
	global_load_dwordx2 v[98:99], v[6:7], off offset:2048
	v_add_co_u32_e32 v6, vcc, s56, v4
	v_lshl_add_u64 v[52:53], v[140:141], 0, s[12:13]
	s_nop 0
	v_addc_co_u32_e32 v7, vcc, 0, v5, vcc
	global_load_dwordx2 v[100:101], v[6:7], off offset:512
	v_add_co_u32_e32 v6, vcc, s33, v4
	s_movk_i32 s0, 0x1000
	s_nop 0
	v_addc_co_u32_e32 v7, vcc, 0, v5, vcc
	global_load_dwordx2 v[102:103], v[6:7], off offset:3072
	v_add_co_u32_e32 v6, vcc, s65, v4
	s_nop 1
	v_addc_co_u32_e32 v7, vcc, 0, v5, vcc
	global_load_dwordx2 v[88:89], v[6:7], off offset:1536
	v_add_co_u32_e32 v6, vcc, s31, v4
	s_nop 1
	v_addc_co_u32_e32 v7, vcc, 0, v5, vcc
	global_load_dwordx2 v[90:91], v[6:7], off
	v_add_co_u32_e32 v6, vcc, s58, v4
	s_nop 1
	v_addc_co_u32_e32 v7, vcc, 0, v5, vcc
	v_add_co_u32_e32 v4, vcc, s59, v4
	s_waitcnt vmcnt(13)
	v_lshlrev_b32_e32 v158, 16, v210
	v_and_b32_e32 v154, 0xffff0000, v210
	v_lshlrev_b32_e32 v150, 16, v211
	v_and_b32_e32 v106, 0xffff0000, v211
	v_lshlrev_b32_e32 v160, 16, v208
	v_and_b32_e32 v156, 0xffff0000, v208
	v_lshlrev_b32_e32 v152, 16, v209
	v_and_b32_e32 v114, 0xffff0000, v209
	v_lshlrev_b32_e32 v164, 16, v104
	v_mov_b32_e32 v161, v164
	v_mov_b32_e32 v159, v160
	v_mov_b32_e32 v155, v156
	v_mov_b32_e32 v151, v152
	v_mov_b32_e32 v107, v114
	v_lshlrev_b32_e32 v162, 16, v118
	s_waitcnt vmcnt(12)
	v_lshlrev_b32_e32 v163, 16, v120
	v_mov_b32_e32 v165, v162
	v_pk_fma_f32 v[182:183], v[162:163], v[80:81], v[84:85] op_sel_hi:[1,0,0]
	v_mov_b32_e32 v166, v163
	v_pk_fma_f32 v[182:183], v[164:165], v[76:77], v[182:183] op_sel_hi:[1,0,1]
	s_waitcnt vmcnt(11)
	v_lshlrev_b32_e32 v167, 16, v122
	v_pk_fma_f32 v[182:183], v[160:161], v[72:73], v[182:183] op_sel_hi:[1,0,1]
	v_mov_b32_e32 v180, v167
	v_pk_fma_f32 v[158:159], v[158:159], v[68:69], v[182:183] op_sel_hi:[1,0,1]
	global_load_dwordx2 v[92:93], v[6:7], off offset:2560
	v_mul_f32_e32 v2, 0xbfb8aa3b, v158
	v_exp_f32_e32 v2, v2
	s_waitcnt vmcnt(11)
	v_lshlrev_b32_e32 v181, 16, v148
	v_addc_co_u32_e32 v5, vcc, 0, v5, vcc
	v_add_f32_e32 v2, 1.0, v2
	v_rcp_f32_e32 v160, v2
	v_mul_f32_e32 v2, 0xbfb8aa3b, v159
	v_exp_f32_e32 v2, v2
	global_load_dwordx2 v[94:95], v[4:5], off offset:1024
	v_add_co_u32_e32 v32, vcc, s0, v52
	v_add_f32_e32 v2, 1.0, v2
	v_rcp_f32_e32 v161, v2
	v_addc_co_u32_e32 v33, vcc, 0, v53, vcc
	v_add_co_u32_e32 v48, vcc, s30, v52
	v_pk_mul_f32 v[158:159], v[158:159], v[160:161]
	v_pk_fma_f32 v[160:161], v[180:181], v[80:81], v[84:85] op_sel_hi:[1,0,0]
	v_cvt_pk_bf16_f32 v158, v158, v159
	v_pk_fma_f32 v[160:161], v[166:167], v[76:77], v[160:161] op_sel_hi:[1,0,1]
	v_addc_co_u32_e32 v49, vcc, 0, v53, vcc
	v_pk_fma_f32 v[160:161], v[162:163], v[72:73], v[160:161] op_sel_hi:[1,0,1]
	s_waitcnt vmcnt(8)
	v_lshlrev_b32_e32 v183, 16, v116
	v_pk_fma_f32 v[160:161], v[164:165], v[68:69], v[160:161] op_sel_hi:[1,0,1]
	v_lshlrev_b32_e32 v165, 16, v112
	v_mul_f32_e32 v2, 0xbfb8aa3b, v160
	v_exp_f32_e32 v2, v2
	v_mov_b32_e32 v182, v165
	s_movk_i32 s0, 0x3000
	v_add_co_u32_e32 v64, vcc, s0, v52
	v_add_f32_e32 v2, 1.0, v2
	v_rcp_f32_e32 v162, v2
	v_mul_f32_e32 v2, 0xbfb8aa3b, v161
	v_exp_f32_e32 v2, v2
	v_addc_co_u32_e32 v65, vcc, 0, v53, vcc
	global_load_dwordx4 v[4:7], v[52:53], off
	global_load_dwordx4 v[8:11], v[52:53], off offset:64
	global_load_dwordx4 v[12:15], v[52:53], off offset:128
	global_load_dwordx4 v[16:19], v[52:53], off offset:192
	v_add_f32_e32 v2, 1.0, v2
	v_rcp_f32_e32 v163, v2
	global_load_dwordx4 v[20:23], v[48:49], off offset:-4096
	global_load_dwordx4 v[24:27], v[32:33], off offset:64
	global_load_dwordx4 v[28:31], v[32:33], off offset:128
	s_nop 0
	global_load_dwordx4 v[32:35], v[32:33], off offset:192
	s_nop 0
	global_load_dwordx4 v[36:39], v[48:49], off
	global_load_dwordx4 v[40:43], v[48:49], off offset:64
	global_load_dwordx4 v[44:47], v[48:49], off offset:128
	s_nop 0
	global_load_dwordx4 v[48:51], v[48:49], off offset:192
	s_nop 0
	global_load_dwordx4 v[52:55], v[64:65], off
	global_load_dwordx4 v[56:59], v[64:65], off offset:64
	global_load_dwordx4 v[60:63], v[64:65], off offset:128
	s_nop 0
	global_load_dwordx4 v[64:67], v[64:65], off offset:192
	s_add_i32 s13, s10, s69
	v_pk_mul_f32 v[160:161], v[160:161], v[162:163]
	v_lshlrev_b32_e32 v163, 16, v110
	v_lshlrev_b32_e32 v162, 16, v108
	v_cvt_pk_bf16_f32 v159, v160, v161
	v_pk_fma_f32 v[160:161], v[162:163], v[80:81], v[84:85] op_sel_hi:[1,0,0]
	v_pk_mov_b32 v[184:185], v[180:181], v[162:163] op_sel:[1,0]
	v_mov_b32_e32 v164, v163
	v_pk_fma_f32 v[160:161], v[184:185], v[76:77], v[160:161] op_sel_hi:[1,0,1]
	s_add_i32 s10, s13, s4
	v_pk_fma_f32 v[160:161], v[180:181], v[72:73], v[160:161] op_sel_hi:[1,0,1]
	s_ashr_i32 s11, s10, 31
	v_pk_fma_f32 v[160:161], v[166:167], v[68:69], v[160:161] op_sel_hi:[1,0,1]
	s_lshl_b64 s[10:11], s[10:11], 2
	v_mul_f32_e32 v2, 0xbfb8aa3b, v160
	v_exp_f32_e32 v2, v2
	s_add_u32 s10, s86, s10
	s_addc_u32 s11, s87, s11
	s_lshl_b32 s14, s13, 9
	v_add_f32_e32 v2, 1.0, v2
	v_rcp_f32_e32 v166, v2
	v_mul_f32_e32 v2, 0xbfb8aa3b, v161
	v_exp_f32_e32 v2, v2
	s_mov_b32 s66, 0
	s_add_i32 s12, s14, 0
	v_add_f32_e32 v2, 1.0, v2
	v_rcp_f32_e32 v167, v2
	s_nop 0
	v_pk_mul_f32 v[160:161], v[160:161], v[166:167]
	v_pk_fma_f32 v[166:167], v[182:183], v[80:81], v[84:85] op_sel_hi:[1,0,0]
	v_cvt_pk_bf16_f32 v160, v160, v161
	v_pk_fma_f32 v[166:167], v[164:165], v[76:77], v[166:167] op_sel_hi:[1,0,1]
	s_nop 0
	v_pk_fma_f32 v[162:163], v[162:163], v[72:73], v[166:167] op_sel_hi:[1,0,1]
	s_nop 0
	v_pk_fma_f32 v[162:163], v[184:185], v[68:69], v[162:163] op_sel_hi:[1,0,1]
	s_nop 0
	v_mul_f32_e32 v2, 0xbfb8aa3b, v162
	v_exp_f32_e32 v2, v2
	s_nop 0
	v_add_f32_e32 v2, 1.0, v2
	v_rcp_f32_e32 v166, v2
	v_mul_f32_e32 v2, 0xbfb8aa3b, v163
	v_exp_f32_e32 v2, v2
	s_nop 0
	v_add_f32_e32 v2, 1.0, v2
	v_rcp_f32_e32 v167, v2
	s_nop 0
	v_pk_mul_f32 v[162:163], v[162:163], v[166:167]
	s_nop 0
	v_cvt_pk_bf16_f32 v161, v162, v163
	ds_write_b128 v178, v[158:161]
	s_waitcnt vmcnt(22)
	v_lshlrev_b32_e32 v161, 16, v98
	v_lshlrev_b32_e32 v160, 16, v96
	v_pk_fma_f32 v[158:159], v[160:161], v[80:81], v[84:85] op_sel_hi:[1,0,0]
	v_pk_mov_b32 v[180:181], v[182:183], v[160:161] op_sel:[1,0]
	s_waitcnt vmcnt(21)
	v_lshlrev_b32_e32 v163, 16, v100
	v_pk_fma_f32 v[158:159], v[180:181], v[76:77], v[158:159] op_sel_hi:[1,0,1]
	s_waitcnt vmcnt(20)
	v_lshlrev_b32_e32 v167, 16, v102
	v_pk_fma_f32 v[158:159], v[182:183], v[72:73], v[158:159] op_sel_hi:[1,0,1]
	v_mov_b32_e32 v166, v163
	v_pk_fma_f32 v[158:159], v[164:165], v[68:69], v[158:159] op_sel_hi:[1,0,1]
	v_mov_b32_e32 v162, v161
	v_mul_f32_e32 v2, 0xbfb8aa3b, v158
	v_exp_f32_e32 v2, v2
	s_waitcnt vmcnt(16)
	global_load_dword v212, v3, s[10:11]
	v_lshlrev_b32_e32 v183, 16, v94
	v_add_f32_e32 v2, 1.0, v2
	v_rcp_f32_e32 v164, v2
	v_mul_f32_e32 v2, 0xbfb8aa3b, v159
	v_exp_f32_e32 v2, v2
	s_nop 0
	v_add_f32_e32 v2, 1.0, v2
	v_rcp_f32_e32 v165, v2
	s_nop 0
	v_pk_mul_f32 v[158:159], v[158:159], v[164:165]
	v_pk_fma_f32 v[164:165], v[166:167], v[80:81], v[84:85] op_sel_hi:[1,0,0]
	v_cvt_pk_bf16_f32 v158, v158, v159
	v_pk_fma_f32 v[164:165], v[162:163], v[76:77], v[164:165] op_sel_hi:[1,0,1]
	s_nop 0
	v_pk_fma_f32 v[160:161], v[160:161], v[72:73], v[164:165] op_sel_hi:[1,0,1]
	s_nop 0
	v_pk_fma_f32 v[160:161], v[180:181], v[68:69], v[160:161] op_sel_hi:[1,0,1]
	v_lshlrev_b32_e32 v181, 16, v92
	v_mul_f32_e32 v2, 0xbfb8aa3b, v160
	v_exp_f32_e32 v2, v2
	v_mov_b32_e32 v182, v181
	v_add_f32_e32 v2, 1.0, v2
	v_rcp_f32_e32 v164, v2
	v_mul_f32_e32 v2, 0xbfb8aa3b, v161
	v_exp_f32_e32 v2, v2
	s_nop 0
	v_add_f32_e32 v2, 1.0, v2
	v_rcp_f32_e32 v165, v2
	s_nop 0
	v_pk_mul_f32 v[160:161], v[160:161], v[164:165]
	v_lshlrev_b32_e32 v164, 16, v88
	v_lshlrev_b32_e32 v165, 16, v90
	v_cvt_pk_bf16_f32 v159, v160, v161
	v_pk_fma_f32 v[160:161], v[164:165], v[80:81], v[84:85] op_sel_hi:[1,0,0]
	v_pk_mov_b32 v[184:185], v[166:167], v[164:165] op_sel:[1,0]
	v_mov_b32_e32 v180, v165
	v_pk_fma_f32 v[160:161], v[184:185], v[76:77], v[160:161] op_sel_hi:[1,0,1]
	s_nop 0
	v_pk_fma_f32 v[160:161], v[166:167], v[72:73], v[160:161] op_sel_hi:[1,0,1]
	s_nop 0
	v_pk_fma_f32 v[160:161], v[162:163], v[68:69], v[160:161] op_sel_hi:[1,0,1]
	s_nop 0
	v_mul_f32_e32 v2, 0xbfb8aa3b, v160
	v_exp_f32_e32 v2, v2
	s_nop 0
	v_add_f32_e32 v2, 1.0, v2
	v_rcp_f32_e32 v162, v2
	v_mul_f32_e32 v2, 0xbfb8aa3b, v161
	v_exp_f32_e32 v2, v2
	s_nop 0
	v_add_f32_e32 v2, 1.0, v2
	v_rcp_f32_e32 v163, v2
	s_nop 0
	v_pk_mul_f32 v[160:161], v[160:161], v[162:163]
	v_pk_fma_f32 v[162:163], v[182:183], v[80:81], v[84:85] op_sel_hi:[1,0,0]
	v_cvt_pk_bf16_f32 v160, v160, v161
	v_pk_fma_f32 v[162:163], v[180:181], v[76:77], v[162:163] op_sel_hi:[1,0,1]
	s_nop 0
	v_pk_fma_f32 v[162:163], v[164:165], v[72:73], v[162:163] op_sel_hi:[1,0,1]
	s_nop 0
	v_pk_fma_f32 v[162:163], v[184:185], v[68:69], v[162:163] op_sel_hi:[1,0,1]
	s_nop 0
	v_mul_f32_e32 v2, 0xbfb8aa3b, v162
	v_exp_f32_e32 v2, v2
	s_nop 0
	v_add_f32_e32 v2, 1.0, v2
	v_rcp_f32_e32 v164, v2
	v_mul_f32_e32 v2, 0xbfb8aa3b, v163
	v_exp_f32_e32 v2, v2
	s_nop 0
	v_add_f32_e32 v2, 1.0, v2
	v_rcp_f32_e32 v165, v2
	s_nop 0
	v_pk_mul_f32 v[162:163], v[162:163], v[164:165]
	s_nop 0
	v_cvt_pk_bf16_f32 v161, v162, v163
	ds_write_b128 v178, v[158:161] offset:16
	v_and_b32_e32 v159, 0xffff0000, v118
	v_and_b32_e32 v161, 0xffff0000, v120
	v_mov_b32_e32 v160, v159
	v_and_b32_e32 v158, 0xffff0000, v104
	v_pk_fma_f32 v[166:167], v[160:161], v[80:81], v[84:85] op_sel:[0,1,1]
	v_mov_b32_e32 v157, v158
	v_pk_fma_f32 v[166:167], v[158:159], v[76:77], v[166:167] op_sel:[0,1,0]
	v_and_b32_e32 v163, 0xffff0000, v122
	v_pk_fma_f32 v[166:167], v[156:157], v[72:73], v[166:167] op_sel:[0,1,0]
	v_and_b32_e32 v165, 0xffff0000, v148
	v_pk_fma_f32 v[154:155], v[154:155], v[68:69], v[166:167] op_sel:[0,1,0]
	v_mov_b32_e32 v164, v163
	v_mul_f32_e32 v2, 0xbfb8aa3b, v154
	v_exp_f32_e32 v2, v2
	v_mov_b32_e32 v162, v161
	v_add_f32_e32 v2, 1.0, v2
	v_rcp_f32_e32 v156, v2
	v_mul_f32_e32 v2, 0xbfb8aa3b, v155
	v_exp_f32_e32 v2, v2
	s_nop 0
	v_add_f32_e32 v2, 1.0, v2
	v_rcp_f32_e32 v157, v2
	s_nop 0
	v_pk_mul_f32 v[154:155], v[154:155], v[156:157]
	v_pk_fma_f32 v[156:157], v[164:165], v[80:81], v[84:85] op_sel:[0,1,1]
	v_cvt_pk_bf16_f32 v154, v154, v155
	v_pk_fma_f32 v[156:157], v[162:163], v[76:77], v[156:157] op_sel:[0,1,0]
	s_nop 0
	v_pk_fma_f32 v[156:157], v[160:161], v[72:73], v[156:157] op_sel:[0,1,0]
	v_and_b32_e32 v161, 0xffff0000, v116
	v_pk_fma_f32 v[156:157], v[158:159], v[68:69], v[156:157] op_sel:[0,1,0]
	s_nop 0
	v_mul_f32_e32 v2, 0xbfb8aa3b, v156
	v_exp_f32_e32 v2, v2
	s_nop 0
	v_add_f32_e32 v2, 1.0, v2
	v_rcp_f32_e32 v158, v2
	v_mul_f32_e32 v2, 0xbfb8aa3b, v157
	v_exp_f32_e32 v2, v2
	s_nop 0
	v_add_f32_e32 v2, 1.0, v2
	v_rcp_f32_e32 v159, v2
	s_nop 0
	v_pk_mul_f32 v[156:157], v[156:157], v[158:159]
	s_nop 0
	v_cvt_pk_bf16_f32 v155, v156, v157
	v_and_b32_e32 v157, 0xffff0000, v110
	v_and_b32_e32 v156, 0xffff0000, v108
	v_pk_fma_f32 v[166:167], v[156:157], v[80:81], v[84:85] op_sel:[0,1,1]
	v_pk_mov_b32 v[180:181], v[164:165], v[156:157] op_sel:[1,0]
	v_and_b32_e32 v159, 0xffff0000, v112
	v_pk_fma_f32 v[166:167], v[180:181], v[76:77], v[166:167] op_sel:[0,1,0]
	v_mov_b32_e32 v160, v159
	v_pk_fma_f32 v[164:165], v[164:165], v[72:73], v[166:167] op_sel:[0,1,0]
	v_mov_b32_e32 v158, v157
	v_pk_fma_f32 v[162:163], v[162:163], v[68:69], v[164:165] op_sel:[0,1,0]
	s_nop 0
	v_mul_f32_e32 v2, 0xbfb8aa3b, v162
	v_exp_f32_e32 v2, v2
	s_nop 0
	v_add_f32_e32 v2, 1.0, v2
	v_rcp_f32_e32 v164, v2
	v_mul_f32_e32 v2, 0xbfb8aa3b, v163
	v_exp_f32_e32 v2, v2
	s_nop 0
	v_add_f32_e32 v2, 1.0, v2
	v_rcp_f32_e32 v165, v2
	s_nop 0
	v_pk_mul_f32 v[162:163], v[162:163], v[164:165]
	v_pk_fma_f32 v[164:165], v[160:161], v[80:81], v[84:85] op_sel:[0,1,1]
	v_cvt_pk_bf16_f32 v162, v162, v163
	v_pk_fma_f32 v[164:165], v[158:159], v[76:77], v[164:165] op_sel:[0,1,0]
	s_nop 0
	v_pk_fma_f32 v[156:157], v[156:157], v[72:73], v[164:165] op_sel:[0,1,0]
	s_nop 0
	v_pk_fma_f32 v[156:157], v[180:181], v[68:69], v[156:157] op_sel:[0,1,0]
	s_nop 0
	v_mul_f32_e32 v2, 0xbfb8aa3b, v156
	v_exp_f32_e32 v2, v2
	s_nop 0
	v_add_f32_e32 v2, 1.0, v2
	v_rcp_f32_e32 v164, v2
	v_mul_f32_e32 v2, 0xbfb8aa3b, v157
	v_exp_f32_e32 v2, v2
	s_nop 0
	v_add_f32_e32 v2, 1.0, v2
	v_rcp_f32_e32 v165, v2
	s_nop 0
	v_pk_mul_f32 v[156:157], v[156:157], v[164:165]
	s_nop 0
	v_cvt_pk_bf16_f32 v163, v156, v157
	ds_write2_b64 v178, v[154:155], v[162:163] offset0:33 offset1:34
	v_and_b32_e32 v155, 0xffff0000, v98
	v_and_b32_e32 v154, 0xffff0000, v96
	v_pk_fma_f32 v[164:165], v[154:155], v[80:81], v[84:85] op_sel:[0,1,1]
	v_pk_mov_b32 v[166:167], v[160:161], v[154:155] op_sel:[1,0]
	v_and_b32_e32 v157, 0xffff0000, v100
	v_pk_fma_f32 v[164:165], v[166:167], v[76:77], v[164:165] op_sel:[0,1,0]
	v_and_b32_e32 v163, 0xffff0000, v102
	v_pk_fma_f32 v[160:161], v[160:161], v[72:73], v[164:165] op_sel:[0,1,0]
	v_mov_b32_e32 v162, v157
	v_pk_fma_f32 v[158:159], v[158:159], v[68:69], v[160:161] op_sel:[0,1,0]
	v_mov_b32_e32 v156, v155
	v_mul_f32_e32 v2, 0xbfb8aa3b, v158
	v_exp_f32_e32 v2, v2
	v_and_b32_e32 v165, 0xffff0000, v94
	v_add_f32_e32 v2, 1.0, v2
	v_rcp_f32_e32 v160, v2
	v_mul_f32_e32 v2, 0xbfb8aa3b, v159
	v_exp_f32_e32 v2, v2
	s_nop 0
	v_add_f32_e32 v2, 1.0, v2
	v_rcp_f32_e32 v161, v2
	s_nop 0
	v_pk_mul_f32 v[158:159], v[158:159], v[160:161]
	v_pk_fma_f32 v[160:161], v[162:163], v[80:81], v[84:85] op_sel:[0,1,1]
	v_cvt_pk_bf16_f32 v158, v158, v159
	v_pk_fma_f32 v[160:161], v[156:157], v[76:77], v[160:161] op_sel:[0,1,0]
	s_nop 0
	v_pk_fma_f32 v[154:155], v[154:155], v[72:73], v[160:161] op_sel:[0,1,0]
	s_nop 0
	v_pk_fma_f32 v[154:155], v[166:167], v[68:69], v[154:155] op_sel:[0,1,0]
	s_nop 0
	v_mul_f32_e32 v2, 0xbfb8aa3b, v154
	v_exp_f32_e32 v2, v2
	s_nop 0
	v_add_f32_e32 v2, 1.0, v2
	v_rcp_f32_e32 v160, v2
	v_mul_f32_e32 v2, 0xbfb8aa3b, v155
	v_exp_f32_e32 v2, v2
	s_nop 0
	v_add_f32_e32 v2, 1.0, v2
	v_rcp_f32_e32 v161, v2
	s_nop 0
	v_pk_mul_f32 v[154:155], v[154:155], v[160:161]
	s_nop 0
	v_cvt_pk_bf16_f32 v159, v154, v155
	v_and_b32_e32 v155, 0xffff0000, v90
	v_and_b32_e32 v154, 0xffff0000, v88
	v_pk_fma_f32 v[166:167], v[154:155], v[80:81], v[84:85] op_sel:[0,1,1]
	v_pk_mov_b32 v[180:181], v[162:163], v[154:155] op_sel:[1,0]
	v_and_b32_e32 v161, 0xffff0000, v92
	v_pk_fma_f32 v[166:167], v[180:181], v[76:77], v[166:167] op_sel:[0,1,0]
	v_mov_b32_e32 v164, v161
	v_pk_fma_f32 v[162:163], v[162:163], v[72:73], v[166:167] op_sel:[0,1,0]
	v_mov_b32_e32 v160, v155
	v_pk_fma_f32 v[156:157], v[156:157], v[68:69], v[162:163] op_sel:[0,1,0]
	v_pk_fma_f32 v[80:81], v[164:165], v[80:81], v[84:85] op_sel:[0,1,1]
	v_mul_f32_e32 v2, 0xbfb8aa3b, v156
	v_exp_f32_e32 v2, v2
	v_pk_fma_f32 v[76:77], v[160:161], v[76:77], v[80:81] op_sel:[0,1,0]
	v_lshlrev_b32_e32 v81, 16, v149
	v_pk_fma_f32 v[72:73], v[154:155], v[72:73], v[76:77] op_sel:[0,1,0]
	v_add_f32_e32 v2, 1.0, v2
	v_rcp_f32_e32 v162, v2
	v_mul_f32_e32 v2, 0xbfb8aa3b, v157
	v_exp_f32_e32 v2, v2
	v_pk_fma_f32 v[68:69], v[180:181], v[68:69], v[72:73] op_sel:[0,1,0]
	v_lshlrev_b32_e32 v77, 16, v123
	v_mov_b32_e32 v80, v77
	v_add_f32_e32 v2, 1.0, v2
	v_rcp_f32_e32 v163, v2
	v_mul_f32_e32 v2, 0xbfb8aa3b, v68
	v_exp_f32_e32 v2, v2
	v_or_b32_e32 v180, s14, v126
	v_pk_mul_f32 v[156:157], v[156:157], v[162:163]
	v_add_f32_e32 v2, 1.0, v2
	v_rcp_f32_e32 v72, v2
	v_mul_f32_e32 v2, 0xbfb8aa3b, v69
	v_exp_f32_e32 v2, v2
	v_cvt_pk_bf16_f32 v156, v156, v157
	v_add_f32_e32 v2, 1.0, v2
	v_rcp_f32_e32 v73, v2
	s_nop 0
	v_pk_mul_f32 v[68:69], v[68:69], v[72:73]
	s_nop 0
	v_cvt_pk_bf16_f32 v157, v68, v69
	v_lshlrev_b32_e32 v68, 16, v119
	v_lshlrev_b32_e32 v69, 16, v121
	v_lshlrev_b32_e32 v72, 16, v105
	v_mov_b32_e32 v73, v68
	v_pk_fma_f32 v[84:85], v[68:69], v[82:83], v[86:87] op_sel_hi:[1,0,0]
	v_mov_b32_e32 v153, v72
	v_pk_fma_f32 v[84:85], v[72:73], v[78:79], v[84:85] op_sel_hi:[1,0,1]
	v_mov_b32_e32 v76, v69
	v_pk_fma_f32 v[84:85], v[152:153], v[74:75], v[84:85] op_sel_hi:[1,0,1]
	ds_write2_b64 v178, v[158:159], v[156:157] offset0:35 offset1:36
	v_pk_fma_f32 v[84:85], v[150:151], v[70:71], v[84:85] op_sel_hi:[1,0,1]
	s_nop 0
	v_mul_f32_e32 v2, 0xbfb8aa3b, v84
	v_exp_f32_e32 v2, v2
	s_nop 0
	v_add_f32_e32 v2, 1.0, v2
	v_rcp_f32_e32 v150, v2
	v_mul_f32_e32 v2, 0xbfb8aa3b, v85
	v_exp_f32_e32 v2, v2
	s_nop 0
	v_add_f32_e32 v2, 1.0, v2
	v_rcp_f32_e32 v151, v2
	s_nop 0
	v_pk_mul_f32 v[84:85], v[84:85], v[150:151]
	s_nop 0
	v_cvt_pk_bf16_f32 v150, v84, v85
	v_pk_fma_f32 v[84:85], v[80:81], v[82:83], v[86:87] op_sel_hi:[1,0,0]
	s_nop 0
	v_pk_fma_f32 v[84:85], v[76:77], v[78:79], v[84:85] op_sel_hi:[1,0,1]
	s_nop 0
	v_pk_fma_f32 v[68:69], v[68:69], v[74:75], v[84:85] op_sel_hi:[1,0,1]
	v_lshlrev_b32_e32 v85, 16, v117
	v_pk_fma_f32 v[68:69], v[72:73], v[70:71], v[68:69] op_sel_hi:[1,0,1]
	s_nop 0
	v_mul_f32_e32 v2, 0xbfb8aa3b, v68
	v_exp_f32_e32 v2, v2
	s_nop 0
	v_add_f32_e32 v2, 1.0, v2
	v_rcp_f32_e32 v72, v2
	v_mul_f32_e32 v2, 0xbfb8aa3b, v69
	v_exp_f32_e32 v2, v2
	s_nop 0
	v_add_f32_e32 v2, 1.0, v2
	v_rcp_f32_e32 v73, v2
	s_nop 0
	v_pk_mul_f32 v[68:69], v[68:69], v[72:73]
	s_nop 0
	v_cvt_pk_bf16_f32 v151, v68, v69
	v_lshlrev_b32_e32 v69, 16, v111
	v_lshlrev_b32_e32 v68, 16, v109
	v_pk_fma_f32 v[152:153], v[68:69], v[82:83], v[86:87] op_sel_hi:[1,0,0]
	v_pk_mov_b32 v[154:155], v[80:81], v[68:69] op_sel:[1,0]
	v_lshlrev_b32_e32 v73, 16, v113
	v_pk_fma_f32 v[152:153], v[154:155], v[78:79], v[152:153] op_sel_hi:[1,0,1]
	v_mov_b32_e32 v84, v73
	v_pk_fma_f32 v[80:81], v[80:81], v[74:75], v[152:153] op_sel_hi:[1,0,1]
	v_mov_b32_e32 v72, v69
	v_pk_fma_f32 v[76:77], v[76:77], v[70:71], v[80:81] op_sel_hi:[1,0,1]
	s_nop 0
	v_mul_f32_e32 v2, 0xbfb8aa3b, v76
	v_exp_f32_e32 v2, v2
	s_nop 0
	v_add_f32_e32 v2, 1.0, v2
	v_rcp_f32_e32 v80, v2
	v_mul_f32_e32 v2, 0xbfb8aa3b, v77
	v_exp_f32_e32 v2, v2
	s_nop 0
	v_add_f32_e32 v2, 1.0, v2
	v_rcp_f32_e32 v81, v2
	s_nop 0
	v_pk_mul_f32 v[76:77], v[76:77], v[80:81]
	s_nop 0
	v_cvt_pk_bf16_f32 v152, v76, v77
	v_pk_fma_f32 v[76:77], v[84:85], v[82:83], v[86:87] op_sel_hi:[1,0,0]
	v_lshlrev_b32_e32 v81, 16, v103
	v_pk_fma_f32 v[76:77], v[72:73], v[78:79], v[76:77] op_sel_hi:[1,0,1]
	s_nop 0
	v_pk_fma_f32 v[68:69], v[68:69], v[74:75], v[76:77] op_sel_hi:[1,0,1]
	s_nop 0
	v_pk_fma_f32 v[68:69], v[154:155], v[70:71], v[68:69] op_sel_hi:[1,0,1]
	s_nop 0
	v_mul_f32_e32 v2, 0xbfb8aa3b, v68
	v_exp_f32_e32 v2, v2
	s_nop 0
	v_add_f32_e32 v2, 1.0, v2
	v_rcp_f32_e32 v76, v2
	v_mul_f32_e32 v2, 0xbfb8aa3b, v69
	v_exp_f32_e32 v2, v2
	s_nop 0
	v_add_f32_e32 v2, 1.0, v2
	v_rcp_f32_e32 v77, v2
	s_nop 0
	v_pk_mul_f32 v[68:69], v[68:69], v[76:77]
	s_nop 0
	v_cvt_pk_bf16_f32 v153, v68, v69
	v_lshlrev_b32_e32 v69, 16, v99
	v_lshlrev_b32_e32 v68, 16, v97
	ds_write_b128 v178, v[150:153] offset:528
	v_pk_fma_f32 v[150:151], v[68:69], v[82:83], v[86:87] op_sel_hi:[1,0,0]
	v_pk_mov_b32 v[152:153], v[84:85], v[68:69] op_sel:[1,0]
	v_lshlrev_b32_e32 v77, 16, v101
	v_pk_fma_f32 v[150:151], v[152:153], v[78:79], v[150:151] op_sel_hi:[1,0,1]
	v_mov_b32_e32 v80, v77
	v_pk_fma_f32 v[84:85], v[84:85], v[74:75], v[150:151] op_sel_hi:[1,0,1]
	v_mov_b32_e32 v76, v69
	v_pk_fma_f32 v[72:73], v[72:73], v[70:71], v[84:85] op_sel_hi:[1,0,1]
	s_nop 0
	v_mul_f32_e32 v2, 0xbfb8aa3b, v72
	v_exp_f32_e32 v2, v2
	s_nop 0
	v_add_f32_e32 v2, 1.0, v2
	v_rcp_f32_e32 v84, v2
	v_mul_f32_e32 v2, 0xbfb8aa3b, v73
	v_exp_f32_e32 v2, v2
	s_nop 0
	v_add_f32_e32 v2, 1.0, v2
	v_rcp_f32_e32 v85, v2
	s_nop 0
	v_pk_mul_f32 v[72:73], v[72:73], v[84:85]
	s_nop 0
	v_cvt_pk_bf16_f32 v150, v72, v73
	v_pk_fma_f32 v[72:73], v[80:81], v[82:83], v[86:87] op_sel_hi:[1,0,0]
	v_lshlrev_b32_e32 v85, 16, v95
	v_pk_fma_f32 v[72:73], v[76:77], v[78:79], v[72:73] op_sel_hi:[1,0,1]
	s_nop 0
	v_pk_fma_f32 v[68:69], v[68:69], v[74:75], v[72:73] op_sel_hi:[1,0,1]
	s_nop 0
	v_pk_fma_f32 v[68:69], v[152:153], v[70:71], v[68:69] op_sel_hi:[1,0,1]
	s_nop 0
	v_mul_f32_e32 v2, 0xbfb8aa3b, v68
	v_exp_f32_e32 v2, v2
	s_nop 0
	v_add_f32_e32 v2, 1.0, v2
	v_rcp_f32_e32 v72, v2
	v_mul_f32_e32 v2, 0xbfb8aa3b, v69
	v_exp_f32_e32 v2, v2
	s_nop 0
	v_add_f32_e32 v2, 1.0, v2
	v_rcp_f32_e32 v73, v2
	s_nop 0
	v_pk_mul_f32 v[68:69], v[68:69], v[72:73]
	s_nop 0
	v_cvt_pk_bf16_f32 v151, v68, v69
	v_lshlrev_b32_e32 v68, 16, v89
	v_lshlrev_b32_e32 v69, 16, v91
	v_pk_fma_f32 v[152:153], v[68:69], v[82:83], v[86:87] op_sel_hi:[1,0,0]
	v_pk_mov_b32 v[154:155], v[80:81], v[68:69] op_sel:[1,0]
	v_lshlrev_b32_e32 v73, 16, v93
	v_pk_fma_f32 v[152:153], v[154:155], v[78:79], v[152:153] op_sel_hi:[1,0,1]
	v_mov_b32_e32 v84, v73
	v_pk_fma_f32 v[80:81], v[80:81], v[74:75], v[152:153] op_sel_hi:[1,0,1]
	v_mov_b32_e32 v72, v69
	v_pk_fma_f32 v[76:77], v[76:77], v[70:71], v[80:81] op_sel_hi:[1,0,1]
	s_nop 0
	v_mul_f32_e32 v2, 0xbfb8aa3b, v76
	v_exp_f32_e32 v2, v2
	s_nop 0
	v_add_f32_e32 v2, 1.0, v2
	v_rcp_f32_e32 v80, v2
	v_mul_f32_e32 v2, 0xbfb8aa3b, v77
	v_exp_f32_e32 v2, v2
	s_nop 0
	v_add_f32_e32 v2, 1.0, v2
	v_rcp_f32_e32 v81, v2
	s_nop 0
	v_pk_mul_f32 v[76:77], v[76:77], v[80:81]
	s_nop 0
	v_cvt_pk_bf16_f32 v152, v76, v77
	v_pk_fma_f32 v[76:77], v[84:85], v[82:83], v[86:87] op_sel_hi:[1,0,0]
	v_and_b32_e32 v81, 0xffff0000, v121
	v_pk_fma_f32 v[72:73], v[72:73], v[78:79], v[76:77] op_sel_hi:[1,0,1]
	v_and_b32_e32 v77, 0xffff0000, v119
	v_pk_fma_f32 v[68:69], v[68:69], v[74:75], v[72:73] op_sel_hi:[1,0,1]
	v_mov_b32_e32 v80, v77
	v_pk_fma_f32 v[68:69], v[154:155], v[70:71], v[68:69] op_sel_hi:[1,0,1]
	v_and_b32_e32 v76, 0xffff0000, v105
	v_mul_f32_e32 v2, 0xbfb8aa3b, v68
	v_exp_f32_e32 v2, v2
	v_mov_b32_e32 v70, v79
	v_mov_b32_e32 v115, v76
	v_mov_b32_e32 v74, v71
	v_add_f32_e32 v2, 1.0, v2
	v_rcp_f32_e32 v72, v2
	v_mul_f32_e32 v2, 0xbfb8aa3b, v69
	v_exp_f32_e32 v2, v2
	v_and_b32_e32 v85, 0xffff0000, v123
	v_and_b32_e32 v105, 0xffff0000, v149
	v_mov_b32_e32 v104, v85
	v_add_f32_e32 v2, 1.0, v2
	v_rcp_f32_e32 v73, v2
	v_mov_b32_e32 v2, v83
	v_mov_b32_e32 v84, v81
	v_pk_mul_f32 v[68:69], v[68:69], v[72:73]
	s_nop 0
	v_cvt_pk_bf16_f32 v153, v68, v69
	v_mov_b32_e32 v68, v87
	v_pk_fma_f32 v[72:73], v[80:81], v[2:3], v[68:69] op_sel_hi:[1,0,0]
	ds_write_b128 v178, v[150:153] offset:544
	v_pk_fma_f32 v[78:79], v[76:77], v[70:71], v[72:73] op_sel_hi:[1,0,1]
	v_mov_b32_e32 v72, v75
	v_pk_fma_f32 v[78:79], v[114:115], v[72:73], v[78:79] op_sel_hi:[1,0,1]
	s_nop 0
	v_pk_fma_f32 v[78:79], v[106:107], v[74:75], v[78:79] op_sel_hi:[1,0,1]
	s_nop 0
	v_mul_f32_e32 v69, 0xbfb8aa3b, v78
	v_exp_f32_e32 v69, v69
	s_nop 0
	v_add_f32_e32 v69, 1.0, v69
	v_rcp_f32_e32 v82, v69
	v_mul_f32_e32 v69, 0xbfb8aa3b, v79
	v_exp_f32_e32 v69, v69
	s_nop 0
	v_add_f32_e32 v69, 1.0, v69
	v_rcp_f32_e32 v83, v69
	s_nop 0
	v_pk_mul_f32 v[78:79], v[78:79], v[82:83]
	v_pk_fma_f32 v[82:83], v[104:105], v[2:3], v[68:69] op_sel_hi:[1,0,0]
	v_cvt_pk_bf16_f32 v78, v78, v79
	v_pk_fma_f32 v[82:83], v[84:85], v[70:71], v[82:83] op_sel_hi:[1,0,1]
	s_nop 0
	v_pk_fma_f32 v[80:81], v[80:81], v[72:73], v[82:83] op_sel_hi:[1,0,1]
	v_and_b32_e32 v83, 0xffff0000, v117
	v_pk_fma_f32 v[76:77], v[76:77], v[74:75], v[80:81] op_sel_hi:[1,0,1]
	s_nop 0
	v_mul_f32_e32 v69, 0xbfb8aa3b, v76
	v_exp_f32_e32 v69, v69
	s_nop 0
	v_add_f32_e32 v69, 1.0, v69
	v_rcp_f32_e32 v80, v69
	v_mul_f32_e32 v69, 0xbfb8aa3b, v77
	v_exp_f32_e32 v69, v69
	s_nop 0
	v_add_f32_e32 v69, 1.0, v69
	v_rcp_f32_e32 v81, v69
	s_nop 0
	v_pk_mul_f32 v[76:77], v[76:77], v[80:81]
	s_nop 0
	v_cvt_pk_bf16_f32 v79, v76, v77
	v_and_b32_e32 v77, 0xffff0000, v111
	v_and_b32_e32 v76, 0xffff0000, v109
	v_pk_fma_f32 v[86:87], v[76:77], v[2:3], v[68:69] op_sel_hi:[1,0,0]
	v_pk_mov_b32 v[106:107], v[104:105], v[76:77] op_sel:[1,0]
	v_and_b32_e32 v81, 0xffff0000, v113
	v_pk_fma_f32 v[86:87], v[106:107], v[70:71], v[86:87] op_sel_hi:[1,0,1]
	v_mov_b32_e32 v82, v81
	v_pk_fma_f32 v[86:87], v[104:105], v[72:73], v[86:87] op_sel_hi:[1,0,1]
	v_mov_b32_e32 v80, v77
	v_pk_fma_f32 v[84:85], v[84:85], v[74:75], v[86:87] op_sel_hi:[1,0,1]
	s_nop 0
	v_mul_f32_e32 v69, 0xbfb8aa3b, v84
	v_exp_f32_e32 v69, v69
	s_nop 0
	v_add_f32_e32 v69, 1.0, v69
	v_rcp_f32_e32 v86, v69
	v_mul_f32_e32 v69, 0xbfb8aa3b, v85
	v_exp_f32_e32 v69, v69
	s_nop 0
	v_add_f32_e32 v69, 1.0, v69
	v_rcp_f32_e32 v87, v69
	s_nop 0
	v_pk_mul_f32 v[84:85], v[84:85], v[86:87]
	v_pk_fma_f32 v[86:87], v[82:83], v[2:3], v[68:69] op_sel_hi:[1,0,0]
	v_cvt_pk_bf16_f32 v84, v84, v85
	v_pk_fma_f32 v[86:87], v[80:81], v[70:71], v[86:87] op_sel_hi:[1,0,1]
	s_nop 0
	v_pk_fma_f32 v[76:77], v[76:77], v[72:73], v[86:87] op_sel_hi:[1,0,1]
	s_nop 0
	v_pk_fma_f32 v[76:77], v[106:107], v[74:75], v[76:77] op_sel_hi:[1,0,1]
	s_nop 0
	v_mul_f32_e32 v69, 0xbfb8aa3b, v76
	v_exp_f32_e32 v69, v69
	s_nop 0
	v_add_f32_e32 v69, 1.0, v69
	v_rcp_f32_e32 v86, v69
	v_mul_f32_e32 v69, 0xbfb8aa3b, v77
	v_exp_f32_e32 v69, v69
	s_nop 0
	v_add_f32_e32 v69, 1.0, v69
	v_rcp_f32_e32 v87, v69
	s_nop 0
	v_pk_mul_f32 v[76:77], v[76:77], v[86:87]
	s_nop 0
	v_cvt_pk_bf16_f32 v85, v76, v77
	v_and_b32_e32 v77, 0xffff0000, v99
	v_and_b32_e32 v76, 0xffff0000, v97
	v_pk_fma_f32 v[86:87], v[76:77], v[2:3], v[68:69] op_sel_hi:[1,0,0]
	v_pk_mov_b32 v[96:97], v[82:83], v[76:77] op_sel:[1,0]
	ds_write2_b64 v178, v[78:79], v[84:85] offset0:99 offset1:100
	v_pk_fma_f32 v[86:87], v[96:97], v[70:71], v[86:87] op_sel_hi:[1,0,1]
	v_and_b32_e32 v79, 0xffff0000, v101
	v_pk_fma_f32 v[82:83], v[82:83], v[72:73], v[86:87] op_sel_hi:[1,0,1]
	v_and_b32_e32 v85, 0xffff0000, v103
	v_pk_fma_f32 v[80:81], v[80:81], v[74:75], v[82:83] op_sel_hi:[1,0,1]
	v_mov_b32_e32 v84, v79
	v_mul_f32_e32 v69, 0xbfb8aa3b, v80
	v_exp_f32_e32 v69, v69
	v_mov_b32_e32 v78, v77
	v_and_b32_e32 v87, 0xffff0000, v95
	v_add_f32_e32 v69, 1.0, v69
	v_rcp_f32_e32 v82, v69
	v_mul_f32_e32 v69, 0xbfb8aa3b, v81
	v_exp_f32_e32 v69, v69
	s_nop 0
	v_add_f32_e32 v69, 1.0, v69
	v_rcp_f32_e32 v83, v69
	s_nop 0
	v_pk_mul_f32 v[80:81], v[80:81], v[82:83]
	v_pk_fma_f32 v[82:83], v[84:85], v[2:3], v[68:69] op_sel_hi:[1,0,0]
	v_cvt_pk_bf16_f32 v80, v80, v81
	v_pk_fma_f32 v[82:83], v[78:79], v[70:71], v[82:83] op_sel_hi:[1,0,1]
	s_nop 0
	v_pk_fma_f32 v[76:77], v[76:77], v[72:73], v[82:83] op_sel_hi:[1,0,1]
	s_nop 0
	v_pk_fma_f32 v[76:77], v[96:97], v[74:75], v[76:77] op_sel_hi:[1,0,1]
	s_nop 0
	v_mul_f32_e32 v69, 0xbfb8aa3b, v76
	v_exp_f32_e32 v69, v69
	s_nop 0
	v_add_f32_e32 v69, 1.0, v69
	v_rcp_f32_e32 v82, v69
	v_mul_f32_e32 v69, 0xbfb8aa3b, v77
	v_exp_f32_e32 v69, v69
	s_nop 0
	v_add_f32_e32 v69, 1.0, v69
	v_rcp_f32_e32 v83, v69
	s_nop 0
	v_pk_mul_f32 v[76:77], v[76:77], v[82:83]
	s_nop 0
	v_cvt_pk_bf16_f32 v81, v76, v77
	v_and_b32_e32 v77, 0xffff0000, v91
	v_and_b32_e32 v76, 0xffff0000, v89
	v_pk_fma_f32 v[88:89], v[76:77], v[2:3], v[68:69] op_sel_hi:[1,0,0]
	v_pk_mov_b32 v[90:91], v[84:85], v[76:77] op_sel:[1,0]
	v_and_b32_e32 v83, 0xffff0000, v93
	v_pk_fma_f32 v[88:89], v[90:91], v[70:71], v[88:89] op_sel_hi:[1,0,1]
	v_mov_b32_e32 v86, v83
	v_pk_fma_f32 v[84:85], v[84:85], v[72:73], v[88:89] op_sel_hi:[1,0,1]
	v_mov_b32_e32 v82, v77
	v_pk_fma_f32 v[78:79], v[78:79], v[74:75], v[84:85] op_sel_hi:[1,0,1]
	s_nop 0
	v_mul_f32_e32 v69, 0xbfb8aa3b, v78
	v_exp_f32_e32 v69, v69
	s_nop 0
	v_add_f32_e32 v69, 1.0, v69
	v_rcp_f32_e32 v84, v69
	v_mul_f32_e32 v69, 0xbfb8aa3b, v79
	v_exp_f32_e32 v69, v69
	s_nop 0
	v_add_f32_e32 v69, 1.0, v69
	v_rcp_f32_e32 v85, v69
	v_pk_fma_f32 v[68:69], v[86:87], v[2:3], v[68:69] op_sel_hi:[1,0,0]
	v_pk_mul_f32 v[78:79], v[78:79], v[84:85]
	v_pk_fma_f32 v[68:69], v[82:83], v[70:71], v[68:69] op_sel_hi:[1,0,1]
	v_cvt_pk_bf16_f32 v78, v78, v79
	v_pk_fma_f32 v[68:69], v[76:77], v[72:73], v[68:69] op_sel_hi:[1,0,1]
	s_nop 0
	v_pk_fma_f32 v[68:69], v[90:91], v[74:75], v[68:69] op_sel_hi:[1,0,1]
	s_nop 0
	v_mul_f32_e32 v2, 0xbfb8aa3b, v68
	v_exp_f32_e32 v2, v2
	s_nop 0
	v_add_f32_e32 v2, 1.0, v2
	v_rcp_f32_e32 v70, v2
	v_mul_f32_e32 v2, 0xbfb8aa3b, v69
	v_exp_f32_e32 v2, v2
	s_nop 0
	v_add_f32_e32 v2, 1.0, v2
	v_rcp_f32_e32 v71, v2
	s_nop 0
	v_pk_mul_f32 v[68:69], v[68:69], v[70:71]
	s_nop 0
	v_cvt_pk_bf16_f32 v79, v68, v69
	ds_write2_b64 v178, v[80:81], v[78:79] offset0:101 offset1:102
	s_waitcnt lgkmcnt(0)
	s_barrier
	s_lshl_b32 s10, s13, 6
	s_ashr_i32 s11, s10, 31
	s_lshl_b32 s13, s22, 4
	s_lshl_b64 s[10:11], s[10:11], 1
	s_add_i32 s13, s61, s13
	v_lshl_add_u64 v[150:151], v[144:145], 0, s[10:11]
	v_lshl_add_u64 v[152:153], v[146:147], 0, s[10:11]
	s_waitcnt vmcnt(0)
	v_mov_b32_e32 v148, v212
	v_mov_b32_e32 v149, v212
	s_branch .LBB0_572
